# v11
# speedup vs baseline: 1.0313x; 1.0105x over previous
.LBB0_54:
	v_exp_f32_e32 v238, v80
	v_exp_f32_e32 v240, v81
	v_exp_f32_e32 v241, v82
	v_exp_f32_e32 v243, v83
	v_exp_f32_e32 v244, v84
	v_exp_f32_e32 v133, v64
	v_exp_f32_e32 v132, v66
	v_add_f32_e32 v64, 0, v238
	v_add_f32_e32 v66, 0, v148
	v_exp_f32_e32 v245, v85
	v_add_f32_e32 v64, v240, v64
	v_add_f32_e32 v66, v149, v66
	v_exp_f32_e32 v239, v86
	v_add_f32_e32 v64, v241, v64
	v_add_f32_e32 v66, v150, v66
	v_exp_f32_e32 v242, v87
	v_add_f32_e32 v64, v243, v64
	v_add_f32_e32 v66, v151, v66
	v_exp_f32_e32 v234, v88
	v_add_f32_e32 v64, v244, v64
	v_add_f32_e32 v66, v155, v66
	v_exp_f32_e32 v235, v89
	v_add_f32_e32 v64, v245, v64
	v_add_f32_e32 v66, v168, v66
	v_exp_f32_e32 v236, v90
	v_add_f32_e32 v64, v239, v64
	v_add_f32_e32 v66, v169, v66
	v_exp_f32_e32 v237, v91
	v_add_f32_e32 v64, v242, v64
	v_add_f32_e32 v66, v170, v66
	v_exp_f32_e32 v230, v92
	v_add_f32_e32 v64, v234, v64
	v_add_f32_e32 v66, v171, v66
	v_exp_f32_e32 v232, v93
	v_add_f32_e32 v64, v235, v64
	v_add_f32_e32 v66, v191, v66
	v_exp_f32_e32 v231, v94
	v_add_f32_e32 v64, v236, v64
	v_add_f32_e32 v66, v192, v66
	v_exp_f32_e32 v233, v95
	v_add_f32_e32 v64, v237, v64
	v_add_f32_e32 v66, v195, v66
	v_add_f32_e32 v64, v230, v64
	v_add_f32_e32 v66, v196, v66
	v_exp_f32_e32 v226, v65
	v_add_f32_e32 v64, v232, v64
	v_add_f32_e32 v66, v197, v66
	v_add_f32_e32 v64, v231, v64
	v_add_f32_e32 v66, v198, v66
	v_exp_f32_e32 v134, v67
	v_add_f32_e32 v64, v233, v64
	v_add_f32_e32 v66, v199, v66
	v_exp_f32_e32 v135, v68
	v_add_f32_e32 v64, v133, v64
	v_add_f32_e32 v66, v200, v66
	v_exp_f32_e32 v227, v69
	v_add_f32_e32 v64, v226, v64
	v_add_f32_e32 v66, v201, v66
	v_mad_i64_i32 v[156:157], s[8:9], v139, s73, 0
	v_mad_i64_i32 v[158:159], s[8:9], v140, s73, 0
	v_mad_i64_i32 v[160:161], s[8:9], v141, s73, 0
	v_mad_i64_i32 v[162:163], s[8:9], v142, s73, 0
	v_mad_i64_i32 v[164:165], s[8:9], v143, s73, 0
	v_mad_i64_i32 v[166:167], s[8:9], v144, s73, 0
	v_exp_f32_e32 v228, v70
	v_add_f32_e32 v64, v132, v64
	v_add_f32_e32 v66, v211, v66
	v_exp_f32_e32 v229, v71
	v_add_f32_e32 v64, v134, v64
	v_add_f32_e32 v66, v212, v66
	v_readlane_b32 s8, v255, 9
	v_exp_f32_e32 v124, v72
	v_add_f32_e32 v64, v135, v64
	v_add_f32_e32 v66, v213, v66
	s_add_u32 s46, s8, s10
	v_readlane_b32 s8, v255, 10
	v_exp_f32_e32 v125, v73
	v_add_f32_e32 v64, v227, v64
	v_add_f32_e32 v66, v214, v66
	s_addc_u32 s47, s8, s11
	v_exp_f32_e32 v126, v74
	v_add_f32_e32 v64, v228, v64
	v_add_f32_e32 v66, v215, v66
	s_add_u32 s20, s78, s10
	v_exp_f32_e32 v127, v75
	v_add_f32_e32 v64, v229, v64
	v_add_f32_e32 v66, v216, v66
	s_addc_u32 s21, s79, s11
	v_exp_f32_e32 v128, v76
	v_add_f32_e32 v64, v124, v64
	v_add_f32_e32 v66, v217, v66
	s_cmp_lg_u32 0, -1
	v_exp_f32_e32 v129, v77
	v_add_f32_e32 v64, v125, v64
	v_add_f32_e32 v66, v218, v66
	s_cselect_b32 s8, 0, 0
	v_exp_f32_e32 v130, v78
	v_add_f32_e32 v64, v126, v64
	v_add_f32_e32 v66, v219, v66
	s_addk_i32 s8, 0x4000
	v_exp_f32_e32 v131, v79
	v_add_f32_e32 v64, v127, v64
	v_add_f32_e32 v66, v220, v66
	s_add_u32 s10, s23, s10
	v_add_f32_e32 v64, v128, v64
	v_add_f32_e32 v66, v221, v66
	s_addc_u32 s11, s22, s11
	v_add_f32_e32 v64, v129, v64
	v_add_f32_e32 v66, v222, v66
	s_add_u32 s77, s18, s10
	v_add_f32_e32 v64, v130, v64
	v_add_f32_e32 v66, v223, v66
	s_addc_u32 s66, s19, s11
	s_lshr_b32 s10, s27, 7
	v_add_f32_e32 v194, v131, v64
	v_bfe_u32 v64, v138, 4, 4
	v_bfe_u32 v65, v138, 3, 4
	v_add_f32_e32 v66, v224, v66
	s_mul_i32 s10, s10, 0xc0000
	v_add_f32_e32 v192, 0, v66
	s_mov_b32 s25, 1
	v_add_u32_e32 v195, s8, v172
	v_cmp_gt_u32_e64 s[8:9], 32, v137
	v_lshl_add_u32 v191, v136, 2, s59
	v_mul_u32_u24_e32 v168, 0x1800, v64
	v_mov_b32_e32 v169, v181
	v_mul_u32_u24_e32 v170, 0x1800, v65
	v_mov_b32_e32 v171, v181
	s_add_u32 s67, s10, 0xffe80000
	s_add_u32 s88, s10, 0xfff40000
	s_mov_b64 s[22:23], 0
	s_waitcnt lgkmcnt(0)
	s_barrier
	s_mov_b32 s100, 0x8000
	s_mov_b32 s101, 0x18800
	s_mov_b32 s89, 0x14000
	s_mov_b32 s25, 0x20800
	v_fma_f32 v192, v192, v193, v194
	v_cvt_pk_bf16_f32 v250, v238, v240
	v_cvt_pk_bf16_f32 v251, v241, v243
	v_cvt_pk_bf16_f32 v252, v244, v245
	v_cvt_pk_bf16_f32 v253, v239, v242
	v_cvt_pk_bf16_f32 v238, v234, v235
	v_cvt_pk_bf16_f32 v239, v236, v237
	v_cvt_pk_bf16_f32 v240, v230, v232
	v_cvt_pk_bf16_f32 v241, v231, v233
	v_cvt_pk_bf16_f32 v242, v133, v226
	v_cvt_pk_bf16_f32 v243, v132, v134
	v_cvt_pk_bf16_f32 v244, v135, v227
	v_cvt_pk_bf16_f32 v245, v228, v229
	v_cvt_pk_bf16_f32 v246, v124, v125
	v_cvt_pk_bf16_f32 v247, v126, v127
	v_cvt_pk_bf16_f32 v248, v128, v129
	v_cvt_pk_bf16_f32 v249, v130, v131
	s_nop 1
	v_permlane32_swap_b32_e32 v250, v252
	v_permlane32_swap_b32_e32 v251, v253
	v_permlane32_swap_b32_e32 v238, v240
	v_permlane32_swap_b32_e32 v239, v241
	v_permlane32_swap_b32_e32 v242, v244
	v_permlane32_swap_b32_e32 v243, v245
	v_permlane32_swap_b32_e32 v246, v248
	v_permlane32_swap_b32_e32 v247, v249
	v_mov_b32_e32 v234, v250
	v_mov_b32_e32 v235, v251
	v_mov_b32_e32 v236, v252
	v_mov_b32_e32 v237, v253
	v_xor_b32_e32 v196, 0x80000000, v190
	v_mov_b32_e32 v197, v196
	v_mov_b32_e32 v198, v196
	v_mov_b32_e32 v199, v196
	v_mov_b32_e32 v200, v196
	v_mov_b32_e32 v201, v196
	v_mov_b32_e32 v202, v196
	v_mov_b32_e32 v203, v196
	v_mov_b32_e32 v204, v196
	v_mov_b32_e32 v205, v196
	v_mov_b32_e32 v206, v196
	v_mov_b32_e32 v207, v196
	v_mov_b32_e32 v208, v196
	v_mov_b32_e32 v209, v196
	v_mov_b32_e32 v210, v196
	v_mov_b32_e32 v211, v196
	v_mov_b32_e32 v253, 1.0
	v_add_u32_e32 v156, v156, v180
	v_add_u32_e32 v158, v158, v180
	v_add_u32_e32 v160, v160, v154
	v_add_u32_e32 v162, v162, v154
	v_add_u32_e32 v164, v164, v180
	v_add_u32_e32 v166, v166, v180
	v_add_u32_e32 v168, v168, v180
	v_add_u32_e32 v170, v170, v154
.LBB0_55:
	v_add_u32_e32 v193, s89, v182
	v_add_u32_e32 v194, s89, v186
	v_add_u32_e32 v232, s89, v187
	v_add_u32_e32 v233, s89, v188
	s_sub_i32 s11, 0x20800, s100
	s_sub_i32 s11, s11, s101
	v_add_u32_e32 v189, s11, v195
	ds_read_b128 v[228:231], v193
	ds_read_b128 v[224:227], v193 offset:4096
	s_waitcnt lgkmcnt(1)
	v_mfma_f32_32x32x16_bf16 v[80:95], v[228:231], v[108:111], v[196:211]
	ds_read_b128 v[228:231], v194
	s_waitcnt lgkmcnt(1)
	v_mfma_f32_32x32x16_bf16 v[64:79], v[224:227], v[108:111], v[196:211]
	ds_read_b128 v[224:227], v194 offset:4096
	s_waitcnt lgkmcnt(1)
	v_mfma_f32_32x32x16_bf16 v[80:95], v[228:231], v[104:107], v[80:95]
	ds_read_b128 v[228:231], v232
	s_waitcnt lgkmcnt(1)
	v_mfma_f32_32x32x16_bf16 v[64:79], v[224:227], v[104:107], v[64:79]
	ds_read_b128 v[224:227], v232 offset:4096
	s_waitcnt lgkmcnt(1)
	v_mfma_f32_32x32x16_bf16 v[80:95], v[228:231], v[100:103], v[80:95]
	ds_read_b128 v[228:231], v233
	s_waitcnt lgkmcnt(1)
	v_mfma_f32_32x32x16_bf16 v[64:79], v[224:227], v[100:103], v[64:79]
	ds_read_b128 v[224:227], v233 offset:4096
	ds_read_b64_tr_b16 v[212:213], v189 offset:0
	ds_read_b64_tr_b16 v[214:215], v189 offset:0x800
	ds_read_b64_tr_b16 v[216:217], v189 offset:0x1000
	ds_read_b64_tr_b16 v[218:219], v189 offset:0x1800
	ds_read_b64_tr_b16 v[220:221], v189 offset:0x2000
	ds_read_b64_tr_b16 v[222:223], v189 offset:0x2800
	s_waitcnt lgkmcnt(7)
	v_mfma_f32_32x32x16_bf16 v[80:95], v[228:231], v[96:99], v[80:95]
	s_waitcnt lgkmcnt(6)
	v_mfma_f32_32x32x16_bf16 v[64:79], v[224:227], v[96:99], v[64:79]
	ds_read_b64_tr_b16 v[224:225], v189 offset:0x3000
	ds_read_b64_tr_b16 v[226:227], v189 offset:0x3800
	s_cmp_eq_u32 s67, s22
	s_cbranch_scc1 .Lda1_sl_last
	s_add_u32 s10, s77, s22
	s_addc_u32 s11, s66, s23
	s_add_u32 s48, s10, 0x126c3400
	s_addc_u32 s49, s11, 0
	s_add_u32 s50, s77, s22
	s_addc_u32 s51, s66, s23
	s_add_u32 s50, s50, 0x126c2c00
	s_addc_u32 s51, s51, 0
	global_load_dwordx4 v[128:131], v156, s[48:49]
	global_load_dwordx4 v[124:127], v158, s[48:49]
	global_load_dwordx4 v[132:135], v160, s[50:51]
	global_load_dwordx4 v[112:115], v166, s[48:49]
	global_load_dwordx4 v[116:119], v164, s[48:49]
	global_load_dwordx4 v[120:123], v162, s[50:51]
	s_branch .LBB0_61

.LBB0_61:
	s_waitcnt lgkmcnt(4)
	v_mfma_f32_32x32x16_bf16 v[0:15], v[234:237], v[212:215], v[0:15]
	ds_read_b64_tr_b16 v[212:213], v189 offset:0x200
	ds_read_b64_tr_b16 v[214:215], v189 offset:0xa00
	v_mfma_f32_32x32x16_bf16 v[0:15], v[238:241], v[216:219], v[0:15]
	ds_read_b64_tr_b16 v[216:217], v189 offset:0x1200
	ds_read_b64_tr_b16 v[218:219], v189 offset:0x1a00
	v_max3_f32 v250, v80, v81, v82
	v_max3_f32 v250, v250, v83, v84
	v_max3_f32 v250, v250, v85, v86
	v_max3_f32 v250, v250, v87, v88
	v_max3_f32 v250, v250, v89, v90
	v_max3_f32 v250, v250, v91, v92
	s_waitcnt lgkmcnt(4)
	v_mfma_f32_32x32x16_bf16 v[0:15], v[242:245], v[220:223], v[0:15]
	ds_read_b64_tr_b16 v[220:221], v189 offset:0x2200
	ds_read_b64_tr_b16 v[222:223], v189 offset:0x2a00
	v_max3_f32 v250, v250, v93, v94
	v_max3_f32 v250, v250, v95, v64
	v_max3_f32 v250, v250, v65, v66
	v_max3_f32 v250, v250, v67, v68
	v_max3_f32 v250, v250, v69, v70
	v_max3_f32 v250, v250, v71, v72
	v_mfma_f32_32x32x16_bf16 v[0:15], v[246:249], v[224:227], v[0:15]
	ds_read_b64_tr_b16 v[224:225], v189 offset:0x3200
	ds_read_b64_tr_b16 v[226:227], v189 offset:0x3a00
	v_max3_f32 v250, v250, v73, v74
	v_max3_f32 v250, v250, v75, v76
	v_max3_f32 v250, v250, v77, v78
	v_max_f32_e32 v250, v250, v79
	v_mov_b32_e32 v251, v250
	s_waitcnt lgkmcnt(4)
	v_mfma_f32_32x32x16_bf16 v[16:31], v[234:237], v[212:215], v[16:31]
	ds_read_b64_tr_b16 v[212:213], v189 offset:0x400
	ds_read_b64_tr_b16 v[214:215], v189 offset:0xc00
	v_permlane32_swap_b32_e32 v250, v251
	v_max_f32_e32 v251, v250, v251
	v_cmp_ge_f32_e32 vcc, s63, v251
	s_cmp_eq_u64 vcc, exec
	s_cbranch_scc0 .Lda1_rare1

.LBB0_66:
	v_add_u32_e32 v189, s100, v153
	s_waitcnt lgkmcnt(1)
	v_mfma_f32_32x32x16_bf16 v[80:95], v[228:231], v[108:111], v[196:211]
	ds_read_b128 v[228:231], v194 offset:8192
	s_waitcnt lgkmcnt(1)
	v_mfma_f32_32x32x16_bf16 v[64:79], v[224:227], v[108:111], v[196:211]
	ds_read_b128 v[224:227], v194 offset:12288
	s_waitcnt lgkmcnt(1)
	v_mfma_f32_32x32x16_bf16 v[80:95], v[228:231], v[104:107], v[80:95]
	ds_read_b128 v[228:231], v232 offset:8192
	s_waitcnt lgkmcnt(1)
	v_mfma_f32_32x32x16_bf16 v[64:79], v[224:227], v[104:107], v[64:79]
	ds_read_b128 v[224:227], v232 offset:12288
	s_waitcnt lgkmcnt(1)
	v_mfma_f32_32x32x16_bf16 v[80:95], v[228:231], v[100:103], v[80:95]
	ds_read_b128 v[228:231], v233 offset:8192
	s_waitcnt lgkmcnt(1)
	v_mfma_f32_32x32x16_bf16 v[64:79], v[224:227], v[100:103], v[64:79]
	ds_read_b128 v[224:227], v233 offset:12288
	ds_read_b64_tr_b16 v[212:213], v189 offset:0
	ds_read_b64_tr_b16 v[214:215], v189 offset:0x800
	ds_read_b64_tr_b16 v[216:217], v189 offset:0x1000
	ds_read_b64_tr_b16 v[218:219], v189 offset:0x1800
	ds_read_b64_tr_b16 v[220:221], v189 offset:0x2000
	ds_read_b64_tr_b16 v[222:223], v189 offset:0x2800
	s_waitcnt lgkmcnt(7)
	v_mfma_f32_32x32x16_bf16 v[80:95], v[228:231], v[96:99], v[80:95]
	s_waitcnt lgkmcnt(6)
	v_mfma_f32_32x32x16_bf16 v[64:79], v[224:227], v[96:99], v[64:79]
	ds_read_b64_tr_b16 v[224:225], v189 offset:0x3000
	ds_read_b64_tr_b16 v[226:227], v189 offset:0x3800
	s_waitcnt lgkmcnt(4)
	v_mfma_f32_32x32x16_bf16 v[0:15], v[136:139], v[212:215], v[0:15]
	ds_read_b64_tr_b16 v[212:213], v189 offset:0x200
	ds_read_b64_tr_b16 v[214:215], v189 offset:0xa00
	v_mfma_f32_32x32x16_bf16 v[0:15], v[140:143], v[216:219], v[0:15]
	ds_read_b64_tr_b16 v[216:217], v189 offset:0x1200
	ds_read_b64_tr_b16 v[218:219], v189 offset:0x1a00
	v_max3_f32 v250, v80, v81, v82
	v_max3_f32 v250, v250, v83, v84
	v_max3_f32 v250, v250, v85, v86
	v_max3_f32 v250, v250, v87, v88
	v_max3_f32 v250, v250, v89, v90
	v_max3_f32 v250, v250, v91, v92
	s_waitcnt lgkmcnt(4)
	v_mfma_f32_32x32x16_bf16 v[0:15], v[144:147], v[220:223], v[0:15]
	ds_read_b64_tr_b16 v[220:221], v189 offset:0x2200
	ds_read_b64_tr_b16 v[222:223], v189 offset:0x2a00
	v_max3_f32 v250, v250, v93, v94
	v_max3_f32 v250, v250, v95, v64
	v_max3_f32 v250, v250, v65, v66
	v_max3_f32 v250, v250, v67, v68
	v_max3_f32 v250, v250, v69, v70
	v_max3_f32 v250, v250, v71, v72
	v_mfma_f32_32x32x16_bf16 v[0:15], v[148:151], v[224:227], v[0:15]
	ds_read_b64_tr_b16 v[224:225], v189 offset:0x3200
	ds_read_b64_tr_b16 v[226:227], v189 offset:0x3a00
	v_max3_f32 v250, v250, v73, v74
	v_max3_f32 v250, v250, v75, v76
	v_max3_f32 v250, v250, v77, v78
	v_max_f32_e32 v250, v250, v79
	v_mov_b32_e32 v251, v250
	s_waitcnt lgkmcnt(4)
	v_mfma_f32_32x32x16_bf16 v[16:31], v[136:139], v[212:215], v[16:31]
	ds_read_b64_tr_b16 v[212:213], v189 offset:0x400
	ds_read_b64_tr_b16 v[214:215], v189 offset:0xc00
	v_permlane32_swap_b32_e32 v250, v251
	v_max_f32_e32 v251, v250, v251
	v_cmp_ge_f32_e32 vcc, s63, v251
	s_cmp_eq_u64 vcc, exec
	s_cbranch_scc0 .Lda1_rare2
.Lda1_cont2:
	v_mfma_f32_32x32x16_bf16 v[16:31], v[140:143], v[216:219], v[16:31]
	ds_read_b64_tr_b16 v[216:217], v189 offset:0x1400
	ds_read_b64_tr_b16 v[218:219], v189 offset:0x1c00
	v_exp_f32_e32 v80, v80
	v_exp_f32_e32 v81, v81
	v_add_f32_e32 v252, 0, v80
	v_exp_f32_e32 v82, v82
	v_add_f32_e32 v252, v81, v252
	v_exp_f32_e32 v83, v83
	v_add_f32_e32 v252, v82, v252
	s_waitcnt lgkmcnt(4)
	v_mfma_f32_32x32x16_bf16 v[16:31], v[144:147], v[220:223], v[16:31]
	ds_read_b64_tr_b16 v[220:221], v189 offset:0x2400
	ds_read_b64_tr_b16 v[222:223], v189 offset:0x2c00
	v_cvt_pk_bf16_f32 v234, v80, v81
	v_exp_f32_e32 v84, v84
	v_add_f32_e32 v252, v83, v252
	v_exp_f32_e32 v85, v85
	v_add_f32_e32 v252, v84, v252
	v_cvt_pk_bf16_f32 v235, v82, v83
	v_exp_f32_e32 v86, v86
	v_add_f32_e32 v252, v85, v252
	v_mfma_f32_32x32x16_bf16 v[16:31], v[148:151], v[224:227], v[16:31]
	ds_read_b64_tr_b16 v[224:225], v189 offset:0x3400
	ds_read_b64_tr_b16 v[226:227], v189 offset:0x3c00
	s_waitcnt vmcnt(0)
	s_sub_i32 s11, s25, 0x10000
	v_add_u32_e32 v193, s101, v173
	v_add_u32_e32 v194, s101, v174
	v_add_u32_e32 v232, s11, v175
	v_exp_f32_e32 v87, v87
	v_add_f32_e32 v252, v86, v252
	v_cvt_pk_bf16_f32 v236, v84, v85
	v_exp_f32_e32 v88, v88
	v_add_f32_e32 v252, v87, v252
	v_exp_f32_e32 v89, v89
	v_add_f32_e32 v252, v88, v252
	v_cvt_pk_bf16_f32 v237, v86, v87
	s_waitcnt lgkmcnt(4)
	v_mfma_f32_32x32x16_bf16 v[32:47], v[136:139], v[212:215], v[32:47]
	ds_read_b64_tr_b16 v[212:213], v189 offset:0x600
	ds_read_b64_tr_b16 v[214:215], v189 offset:0xe00
	ds_write_b128 v193, v[128:131]
	v_exp_f32_e32 v90, v90
	v_add_f32_e32 v252, v89, v252
	v_exp_f32_e32 v91, v91
	v_permlane32_swap_b32_e32 v234, v236
	v_permlane32_swap_b32_e32 v235, v237
	v_add_f32_e32 v252, v90, v252
	v_cvt_pk_bf16_f32 v238, v88, v89
	v_exp_f32_e32 v92, v92
	v_mfma_f32_32x32x16_bf16 v[32:47], v[140:143], v[216:219], v[32:47]
	ds_read_b64_tr_b16 v[216:217], v189 offset:0x1600
	ds_read_b64_tr_b16 v[218:219], v189 offset:0x1e00
	ds_write_b128 v194, v[124:127]
	v_add_f32_e32 v252, v91, v252
	v_exp_f32_e32 v93, v93
	v_add_f32_e32 v252, v92, v252
	v_cvt_pk_bf16_f32 v239, v90, v91
	v_exp_f32_e32 v94, v94
	v_add_f32_e32 v252, v93, v252
	v_exp_f32_e32 v95, v95
	v_add_f32_e32 v252, v94, v252
	s_waitcnt lgkmcnt(6)
	v_mfma_f32_32x32x16_bf16 v[32:47], v[144:147], v[220:223], v[32:47]
	ds_read_b64_tr_b16 v[220:221], v189 offset:0x2600
	ds_read_b64_tr_b16 v[222:223], v189 offset:0x2e00
	ds_write_b128 v193, v[112:115] offset:16384
	v_cvt_pk_bf16_f32 v240, v92, v93
	v_exp_f32_e32 v64, v64
	v_add_f32_e32 v252, v95, v252
	v_exp_f32_e32 v65, v65
	v_add_f32_e32 v252, v64, v252
	v_cvt_pk_bf16_f32 v241, v94, v95
	v_exp_f32_e32 v66, v66
	v_add_f32_e32 v252, v65, v252
	v_mfma_f32_32x32x16_bf16 v[32:47], v[148:151], v[224:227], v[32:47]
	ds_read_b64_tr_b16 v[224:225], v189 offset:0x3600
	ds_read_b64_tr_b16 v[226:227], v189 offset:0x3e00
	ds_write_b128 v194, v[116:119] offset:16384
	v_exp_f32_e32 v67, v67
	v_permlane32_swap_b32_e32 v238, v240
	v_permlane32_swap_b32_e32 v239, v241
	v_add_f32_e32 v252, v66, v252
	v_cvt_pk_bf16_f32 v242, v64, v65
	v_exp_f32_e32 v68, v68
	v_add_f32_e32 v252, v67, v252
	v_exp_f32_e32 v69, v69
	s_waitcnt lgkmcnt(7)
	v_mfma_f32_32x32x16_bf16 v[48:63], v[136:139], v[212:215], v[48:63]
	ds_write_b128 v232, v[132:135]
	v_add_f32_e32 v252, v68, v252
	v_cvt_pk_bf16_f32 v243, v66, v67
	v_exp_f32_e32 v70, v70
	v_add_f32_e32 v252, v69, v252
	v_exp_f32_e32 v71, v71
	v_add_f32_e32 v252, v70, v252
	v_cvt_pk_bf16_f32 v244, v68, v69
	v_exp_f32_e32 v72, v72
	v_mfma_f32_32x32x16_bf16 v[48:63], v[140:143], v[216:219], v[48:63]
	ds_write_b128 v232, v[120:123] offset:8192
	v_add_f32_e32 v252, v71, v252
	v_exp_f32_e32 v73, v73
	v_add_f32_e32 v252, v72, v252
	v_cvt_pk_bf16_f32 v245, v70, v71
	v_exp_f32_e32 v74, v74
	v_add_f32_e32 v252, v73, v252
	v_exp_f32_e32 v75, v75
	v_permlane32_swap_b32_e32 v242, v244
	s_waitcnt lgkmcnt(3)
	v_mfma_f32_32x32x16_bf16 v[48:63], v[144:147], v[220:223], v[48:63]
	v_permlane32_swap_b32_e32 v243, v245
	v_add_f32_e32 v252, v74, v252
	v_cvt_pk_bf16_f32 v246, v72, v73
	v_exp_f32_e32 v76, v76
	v_add_f32_e32 v252, v75, v252
	v_exp_f32_e32 v77, v77
	v_add_f32_e32 v252, v76, v252
	v_cvt_pk_bf16_f32 v247, v74, v75
	v_exp_f32_e32 v78, v78
	v_mfma_f32_32x32x16_bf16 v[48:63], v[148:151], v[224:227], v[48:63]
	v_add_f32_e32 v252, v77, v252
	v_exp_f32_e32 v79, v79
	v_add_f32_e32 v252, v78, v252
	v_cvt_pk_bf16_f32 v248, v76, v77
	v_add_f32_e32 v252, v79, v252
	v_cvt_pk_bf16_f32 v249, v78, v79
	v_fma_f32 v192, v192, v253, v252
	s_nop 0
	s_nop 0
	v_permlane32_swap_b32_e32 v246, v248
	v_permlane32_swap_b32_e32 v247, v249

.LBB0_71:
	s_sub_i32 s10, 0x20800, s100
	s_sub_i32 s10, s10, s101
	s_sub_i32 s11, 0x44800, s89
	s_sub_i32 s11, s11, s25
	s_mov_b32 s100, s101
	s_mov_b32 s101, s10
	s_mov_b32 s89, s25
	s_mov_b32 s25, s11
	s_add_u32 s22, s22, 0xc0000
	s_addc_u32 s23, s23, 0
	s_cmp_eq_u32 s88, s22
	s_waitcnt lgkmcnt(0)
	s_barrier
	s_cbranch_scc1 .LBB0_76
	s_branch .LBB0_55

.LBB0_76:
	v_mov_b32_e32 v80, 0
	v_mov_b32_e32 v137, 1.0
	v_mov_b32_e32 v206, 0x48f42400
	v_mov_b32_e32 v202, 0x7f800000
	v_mov_b32_e32 v203, 0x37000000
	v_mov_b32_e32 v204, 0xf149f2ca
	v_mov_b32_e32 v205, 1
	v_mov_b32_e32 v210, 0x7fc00000
	s_sub_i32 s10, s89, 0x10000
	v_add_u32_e32 v177, s10, v177
	v_add_u32_e32 v176, s10, v176
	v_add_u32_e32 v178, s10, v178
	v_add_u32_e32 v179, s10, v179
	v_add_u32_e32 v153, s100, v153
	ds_read_b128 v[82:85], v177
	v_xor_b32_e32 v64, 0x80000000, v190
	v_mov_b32_e32 v65, v64
	v_mov_b32_e32 v66, v64
	v_mov_b32_e32 v67, v64
	v_mov_b32_e32 v68, v64
	v_mov_b32_e32 v69, v64
	v_mov_b32_e32 v70, v64
	v_mov_b32_e32 v71, v64
	v_mov_b32_e32 v72, v64
	v_mov_b32_e32 v73, v64
	v_mov_b32_e32 v74, v64
	v_mov_b32_e32 v75, v64
	v_mov_b32_e32 v76, v64
	v_mov_b32_e32 v77, v64
	v_mov_b32_e32 v78, v64
	v_mov_b32_e32 v79, v64
	s_nop 0
	s_nop 0
	s_waitcnt lgkmcnt(0)
	v_mfma_f32_32x32x16_bf16 v[64:79], v[82:85], v[108:111], v[64:79]
	ds_read_b128 v[82:85], v176
	s_nop 0
	s_nop 0
	s_nop 0
	s_nop 0
	s_nop 0
	s_waitcnt lgkmcnt(0)
	v_mfma_f32_32x32x16_bf16 v[64:79], v[82:85], v[104:107], v[64:79]
	ds_read_b128 v[82:85], v178
	ds_read_b128 v[86:89], v179
	s_waitcnt lgkmcnt(1)
	v_mfma_f32_32x32x16_bf16 v[64:79], v[82:85], v[100:103], v[64:79]
	s_nop 0
	s_nop 0
	s_nop 0
	s_nop 0
	s_nop 0
	s_nop 0
	s_nop 0
	s_waitcnt lgkmcnt(0)
	v_mfma_f32_32x32x16_bf16 v[64:79], v[86:89], v[96:99], v[64:79]
	s_nop 0
	s_nop 0
	s_nop 0
	s_nop 0
	s_nop 0
	s_nop 0
	s_nop 5
	s_nop 0
	s_nop 0
	s_nop 0
	s_nop 0
	s_nop 0
	s_nop 0
	s_nop 0
	s_nop 0
	s_sub_i32 s10, 0x20800, s100
	s_sub_i32 s10, s10, s101
	s_add_i32 s10, s10, 0x4000
	v_add_u32_e32 v72, s10, v172
	ds_read_b64_tr_b16 v[94:95], v72 offset:0
	ds_read_b64_tr_b16 v[96:97], v72 offset:0x800
	ds_read_b64_tr_b16 v[98:99], v72 offset:0x1000
	ds_read_b64_tr_b16 v[100:101], v72 offset:0x1800
	ds_read_b64_tr_b16 v[102:103], v72 offset:0x2000
	ds_read_b64_tr_b16 v[104:105], v72 offset:0x2800
	ds_read_b64_tr_b16 v[106:107], v72 offset:0x3000
	ds_read_b64_tr_b16 v[108:109], v72 offset:0x3800
	s_waitcnt lgkmcnt(0)
	s_nop 0
	v_mfma_f32_32x32x16_bf16 v[0:15], v[234:237], v[94:97], v[0:15]
	ds_read_b64_tr_b16 v[94:95], v72 offset:0x200
	ds_read_b64_tr_b16 v[96:97], v72 offset:0xa00
	v_mfma_f32_32x32x16_bf16 v[0:15], v[238:241], v[98:101], v[0:15]
	ds_read_b64_tr_b16 v[98:99], v72 offset:0x1200
	ds_read_b64_tr_b16 v[100:101], v72 offset:0x1a00
	v_mfma_f32_32x32x16_bf16 v[0:15], v[242:245], v[102:105], v[0:15]
	ds_read_b64_tr_b16 v[102:103], v72 offset:0x2200
	ds_read_b64_tr_b16 v[104:105], v72 offset:0x2a00
	v_mfma_f32_32x32x16_bf16 v[0:15], v[246:249], v[106:109], v[0:15]
	ds_read_b64_tr_b16 v[106:107], v72 offset:0x3200
	ds_read_b64_tr_b16 v[108:109], v72 offset:0x3a00
	s_waitcnt lgkmcnt(0)
	v_mfma_f32_32x32x16_bf16 v[16:31], v[234:237], v[94:97], v[16:31]
	ds_read_b64_tr_b16 v[94:95], v72 offset:0x400
	ds_read_b64_tr_b16 v[96:97], v72 offset:0xc00
	v_mfma_f32_32x32x16_bf16 v[16:31], v[238:241], v[98:101], v[16:31]
	ds_read_b64_tr_b16 v[98:99], v72 offset:0x1400
	ds_read_b64_tr_b16 v[100:101], v72 offset:0x1c00
	v_mfma_f32_32x32x16_bf16 v[16:31], v[242:245], v[102:105], v[16:31]
	ds_read_b64_tr_b16 v[102:103], v72 offset:0x2400
	ds_read_b64_tr_b16 v[104:105], v72 offset:0x2c00
	v_mfma_f32_32x32x16_bf16 v[16:31], v[246:249], v[106:109], v[16:31]
	ds_read_b64_tr_b16 v[106:107], v72 offset:0x3400
	ds_read_b64_tr_b16 v[108:109], v72 offset:0x3c00
	s_waitcnt lgkmcnt(0)
	v_mfma_f32_32x32x16_bf16 v[32:47], v[234:237], v[94:97], v[32:47]
	ds_read_b64_tr_b16 v[94:95], v72 offset:0x600
	ds_read_b64_tr_b16 v[96:97], v72 offset:0xe00
	v_mfma_f32_32x32x16_bf16 v[32:47], v[238:241], v[98:101], v[32:47]
	ds_read_b64_tr_b16 v[98:99], v72 offset:0x1600
	ds_read_b64_tr_b16 v[100:101], v72 offset:0x1e00
	v_mfma_f32_32x32x16_bf16 v[32:47], v[242:245], v[102:105], v[32:47]
	ds_read_b64_tr_b16 v[102:103], v72 offset:0x2600
	ds_read_b64_tr_b16 v[104:105], v72 offset:0x2e00
	v_mfma_f32_32x32x16_bf16 v[32:47], v[246:249], v[106:109], v[32:47]
	ds_read_b64_tr_b16 v[106:107], v72 offset:0x3600
	ds_read_b64_tr_b16 v[108:109], v72 offset:0x3e00
	s_waitcnt lgkmcnt(0)
	v_mfma_f32_32x32x16_bf16 v[48:63], v[234:237], v[94:97], v[48:63]
	v_max3_f32 v72, v64, v65, v66
	v_max3_f32 v72, v72, v67, v68
	v_max3_f32 v72, v72, v69, v70
	v_mov_b32_e32 v73, 0xf149f2ca
	v_max3_f32 v72, v72, v71, v73
	v_mov_b32_e32 v78, v72
	s_nop 1
	v_permlane32_swap_b32_e32 v72, v78
	v_mfma_f32_32x32x16_bf16 v[48:63], v[238:241], v[98:101], v[48:63]
	v_max_f32_e32 v72, v72, v72
	v_mfma_f32_32x32x16_bf16 v[48:63], v[242:245], v[102:105], v[48:63]
	v_max_f32_e32 v74, v78, v78
	v_max_f32_e32 v74, v72, v74
	v_cmp_ge_f32_e32 vcc, s63, v74
	s_cmp_eq_u64 vcc, exec
	v_mov_b32_e32 v72, 1.0
	v_mfma_f32_32x32x16_bf16 v[48:63], v[246:249], v[106:109], v[48:63]
	s_cbranch_scc0 .LBB0_145

.LBB0_90:
	v_exp_f32_e32 v238, v80
	v_exp_f32_e32 v240, v81
	v_exp_f32_e32 v241, v82
	v_exp_f32_e32 v243, v83
	v_exp_f32_e32 v244, v84
	v_exp_f32_e32 v133, v64
	v_exp_f32_e32 v132, v66
	v_add_f32_e32 v64, 0, v238
	v_add_f32_e32 v66, 0, v145
	v_exp_f32_e32 v245, v85
	v_add_f32_e32 v64, v240, v64
	v_add_f32_e32 v66, v146, v66
	v_exp_f32_e32 v239, v86
	v_add_f32_e32 v64, v241, v64
	v_add_f32_e32 v66, v147, v66
	v_exp_f32_e32 v242, v87
	v_add_f32_e32 v64, v243, v64
	v_add_f32_e32 v66, v148, v66
	v_exp_f32_e32 v234, v88
	v_add_f32_e32 v64, v244, v64
	v_add_f32_e32 v66, v149, v66
	v_exp_f32_e32 v235, v89
	v_add_f32_e32 v64, v245, v64
	v_add_f32_e32 v66, v150, v66
	v_exp_f32_e32 v236, v90
	v_add_f32_e32 v64, v239, v64
	v_add_f32_e32 v66, v151, v66
	v_exp_f32_e32 v237, v91
	v_add_f32_e32 v64, v242, v64
	v_add_f32_e32 v66, v155, v66
	v_exp_f32_e32 v230, v92
	v_add_f32_e32 v64, v234, v64
	v_add_f32_e32 v66, v168, v66
	v_exp_f32_e32 v232, v93
	v_add_f32_e32 v64, v235, v64
	v_add_f32_e32 v66, v169, v66
	v_exp_f32_e32 v231, v94
	v_add_f32_e32 v64, v236, v64
	v_add_f32_e32 v66, v170, v66
	v_exp_f32_e32 v233, v95
	v_add_f32_e32 v64, v237, v64
	v_add_f32_e32 v66, v171, v66
	v_add_f32_e32 v64, v230, v64
	v_add_f32_e32 v66, v191, v66
	v_exp_f32_e32 v226, v65
	v_add_f32_e32 v64, v232, v64
	v_add_f32_e32 v66, v192, v66
	v_add_f32_e32 v64, v231, v64
	v_add_f32_e32 v66, v195, v66
	v_exp_f32_e32 v134, v67
	v_add_f32_e32 v64, v233, v64
	v_add_f32_e32 v66, v196, v66
	v_exp_f32_e32 v135, v68
	v_add_f32_e32 v64, v133, v64
	v_add_f32_e32 v66, v197, v66
	v_exp_f32_e32 v227, v69
	v_add_f32_e32 v64, v226, v64
	v_add_f32_e32 v66, v198, v66
	v_exp_f32_e32 v228, v70
	v_add_f32_e32 v64, v132, v64
	v_add_f32_e32 v66, v199, v66
	v_exp_f32_e32 v229, v71
	v_add_f32_e32 v64, v134, v64
	v_add_f32_e32 v66, v200, v66
	v_exp_f32_e32 v124, v72
	v_add_f32_e32 v64, v135, v64
	v_add_f32_e32 v66, v201, v66
	v_exp_f32_e32 v125, v73
	v_add_f32_e32 v64, v227, v64
	v_add_f32_e32 v66, v211, v66
	v_exp_f32_e32 v126, v74
	v_add_f32_e32 v64, v228, v64
	v_add_f32_e32 v66, v212, v66
	v_exp_f32_e32 v127, v75
	v_add_f32_e32 v64, v229, v64
	v_add_f32_e32 v66, v213, v66
	v_exp_f32_e32 v128, v76
	v_add_f32_e32 v64, v124, v64
	v_add_f32_e32 v66, v214, v66
	v_exp_f32_e32 v129, v77
	v_add_f32_e32 v64, v125, v64
	v_add_f32_e32 v66, v215, v66
	v_exp_f32_e32 v130, v78
	v_add_f32_e32 v64, v126, v64
	v_add_f32_e32 v66, v216, v66
	v_exp_f32_e32 v131, v79
	v_add_f32_e32 v64, v127, v64
	v_add_f32_e32 v66, v217, v66
	s_add_u32 s38, s46, 0x80
	v_add_f32_e32 v64, v128, v64
	v_add_f32_e32 v66, v218, v66
	s_addc_u32 s39, s47, 0
	v_mad_i64_i32 v[156:157], s[8:9], v138, s73, 0
	v_mad_i64_i32 v[158:159], s[8:9], v139, s73, 0
	v_mad_i64_i32 v[160:161], s[8:9], v140, s73, 0
	v_mad_i64_i32 v[162:163], s[8:9], v142, s73, 0
	v_mad_i64_i32 v[164:165], s[8:9], v143, s73, 0
	v_mad_i64_i32 v[166:167], s[8:9], v144, s73, 0
	v_add_f32_e32 v64, v129, v64
	v_add_f32_e32 v66, v219, v66
	s_cmp_lg_u32 0, -1
	v_add_f32_e32 v64, v130, v64
	v_add_f32_e32 v66, v220, v66
	s_cselect_b32 s8, 0, 0
	v_add_f32_e32 v194, v131, v64
	v_bfe_u32 v64, v137, 4, 4
	v_bfe_u32 v65, v137, 3, 4
	v_add_f32_e32 v66, v221, v66
	s_addk_i32 s8, 0x4000
	v_add_f32_e32 v192, 0, v66
	v_add_u32_e32 v195, s8, v188
	v_cmp_gt_u32_e64 s[8:9], 32, v141
	v_lshl_add_u32 v191, v136, 2, s59
	v_mul_u32_u24_e32 v168, 0x1800, v64
	v_mov_b32_e32 v169, v181
	v_mul_u32_u24_e32 v170, 0x1800, v65
	v_mov_b32_e32 v171, v181
	s_mov_b32 s23, 1
	s_mov_b64 s[40:41], 0
	s_waitcnt lgkmcnt(0)
	s_barrier
	s_mov_b32 s100, 0x8000
	s_mov_b32 s101, 0x18800
	s_mov_b32 s46, 0x14000
	s_mov_b32 s23, 0x20800
	v_fma_f32 v192, v192, v193, v194
	v_cvt_pk_bf16_f32 v250, v238, v240
	v_cvt_pk_bf16_f32 v251, v241, v243
	v_cvt_pk_bf16_f32 v252, v244, v245
	v_cvt_pk_bf16_f32 v253, v239, v242
	v_cvt_pk_bf16_f32 v238, v234, v235
	v_cvt_pk_bf16_f32 v239, v236, v237
	v_cvt_pk_bf16_f32 v240, v230, v232
	v_cvt_pk_bf16_f32 v241, v231, v233
	v_cvt_pk_bf16_f32 v242, v133, v226
	v_cvt_pk_bf16_f32 v243, v132, v134
	v_cvt_pk_bf16_f32 v244, v135, v227
	v_cvt_pk_bf16_f32 v245, v228, v229
	v_cvt_pk_bf16_f32 v246, v124, v125
	v_cvt_pk_bf16_f32 v247, v126, v127
	v_cvt_pk_bf16_f32 v248, v128, v129
	v_cvt_pk_bf16_f32 v249, v130, v131
	s_nop 1
	v_permlane32_swap_b32_e32 v250, v252
	v_permlane32_swap_b32_e32 v251, v253
	v_permlane32_swap_b32_e32 v238, v240
	v_permlane32_swap_b32_e32 v239, v241
	v_permlane32_swap_b32_e32 v242, v244
	v_permlane32_swap_b32_e32 v243, v245
	v_permlane32_swap_b32_e32 v246, v248
	v_permlane32_swap_b32_e32 v247, v249
	v_mov_b32_e32 v234, v250
	v_mov_b32_e32 v235, v251
	v_mov_b32_e32 v236, v252
	v_mov_b32_e32 v237, v253
	v_xor_b32_e32 v196, 0x80000000, v190
	v_mov_b32_e32 v197, v196
	v_mov_b32_e32 v198, v196
	v_mov_b32_e32 v199, v196
	v_mov_b32_e32 v200, v196
	v_mov_b32_e32 v201, v196
	v_mov_b32_e32 v202, v196
	v_mov_b32_e32 v203, v196
	v_mov_b32_e32 v204, v196
	v_mov_b32_e32 v205, v196
	v_mov_b32_e32 v206, v196
	v_mov_b32_e32 v207, v196
	v_mov_b32_e32 v208, v196
	v_mov_b32_e32 v209, v196
	v_mov_b32_e32 v210, v196
	v_mov_b32_e32 v211, v196
	v_mov_b32_e32 v253, 1.0
	v_add_u32_e32 v156, v156, v180
	v_add_u32_e32 v158, v158, v180
	v_add_u32_e32 v160, v160, v154
	v_add_u32_e32 v162, v162, v154
	v_add_u32_e32 v164, v164, v180
	v_add_u32_e32 v166, v166, v180
	v_add_u32_e32 v168, v168, v180
	v_add_u32_e32 v170, v170, v154
.LBB0_91:
	v_add_u32_e32 v193, s46, v175
	v_add_u32_e32 v194, s46, v182
	v_add_u32_e32 v232, s46, v186
	v_add_u32_e32 v233, s46, v187
	s_sub_i32 s11, 0x20800, s100
	s_sub_i32 s11, s11, s101
	v_add_u32_e32 v189, s11, v195
	ds_read_b128 v[228:231], v193
	ds_read_b128 v[224:227], v193 offset:4096
	s_waitcnt lgkmcnt(1)
	v_mfma_f32_32x32x16_bf16 v[80:95], v[228:231], v[108:111], v[196:211]
	ds_read_b128 v[228:231], v194
	s_waitcnt lgkmcnt(1)
	v_mfma_f32_32x32x16_bf16 v[64:79], v[224:227], v[108:111], v[196:211]
	ds_read_b128 v[224:227], v194 offset:4096
	s_waitcnt lgkmcnt(1)
	v_mfma_f32_32x32x16_bf16 v[80:95], v[228:231], v[104:107], v[80:95]
	ds_read_b128 v[228:231], v232
	s_waitcnt lgkmcnt(1)
	v_mfma_f32_32x32x16_bf16 v[64:79], v[224:227], v[104:107], v[64:79]
	ds_read_b128 v[224:227], v232 offset:4096
	s_waitcnt lgkmcnt(1)
	v_mfma_f32_32x32x16_bf16 v[80:95], v[228:231], v[100:103], v[80:95]
	ds_read_b128 v[228:231], v233
	s_waitcnt lgkmcnt(1)
	v_mfma_f32_32x32x16_bf16 v[64:79], v[224:227], v[100:103], v[64:79]
	ds_read_b128 v[224:227], v233 offset:4096
	ds_read_b64_tr_b16 v[212:213], v189 offset:0
	ds_read_b64_tr_b16 v[214:215], v189 offset:0x800
	ds_read_b64_tr_b16 v[216:217], v189 offset:0x1000
	ds_read_b64_tr_b16 v[218:219], v189 offset:0x1800
	ds_read_b64_tr_b16 v[220:221], v189 offset:0x2000
	ds_read_b64_tr_b16 v[222:223], v189 offset:0x2800
	s_waitcnt lgkmcnt(7)
	v_mfma_f32_32x32x16_bf16 v[80:95], v[228:231], v[96:99], v[80:95]
	s_waitcnt lgkmcnt(6)
	v_mfma_f32_32x32x16_bf16 v[64:79], v[224:227], v[96:99], v[64:79]
	ds_read_b64_tr_b16 v[224:225], v189 offset:0x3000
	ds_read_b64_tr_b16 v[226:227], v189 offset:0x3800
	s_cmp_eq_u32 s67, s40
	s_cbranch_scc1 .Lda2_sl_last
	s_add_u32 s10, s77, s40
	s_addc_u32 s11, s66, s41
	s_add_u32 s42, s10, 0x126c3400
	s_addc_u32 s43, s11, 0
	s_add_u32 s25, s77, s40
	s_addc_u32 s45, s66, s41
	s_add_u32 s44, s25, 0x126c2c80
	s_addc_u32 s45, s45, 0
	global_load_dwordx4 v[128:131], v156, s[42:43]
	global_load_dwordx4 v[124:127], v158, s[42:43]
	global_load_dwordx4 v[132:135], v160, s[44:45]
	global_load_dwordx4 v[112:115], v166, s[42:43]
	global_load_dwordx4 v[116:119], v164, s[42:43]
	global_load_dwordx4 v[120:123], v162, s[44:45]
	s_branch .LBB0_97

.Lda2_cont2:
	v_mfma_f32_32x32x16_bf16 v[16:31], v[140:143], v[216:219], v[16:31]
	ds_read_b64_tr_b16 v[216:217], v189 offset:0x1400
	ds_read_b64_tr_b16 v[218:219], v189 offset:0x1c00
	v_exp_f32_e32 v80, v80
	v_exp_f32_e32 v81, v81
	v_add_f32_e32 v252, 0, v80
	v_exp_f32_e32 v82, v82
	v_add_f32_e32 v252, v81, v252
	v_exp_f32_e32 v83, v83
	v_add_f32_e32 v252, v82, v252
	s_waitcnt lgkmcnt(4)
	v_mfma_f32_32x32x16_bf16 v[16:31], v[144:147], v[220:223], v[16:31]
	ds_read_b64_tr_b16 v[220:221], v189 offset:0x2400
	ds_read_b64_tr_b16 v[222:223], v189 offset:0x2c00
	v_cvt_pk_bf16_f32 v234, v80, v81
	v_exp_f32_e32 v84, v84
	v_add_f32_e32 v252, v83, v252
	v_exp_f32_e32 v85, v85
	v_add_f32_e32 v252, v84, v252
	v_cvt_pk_bf16_f32 v235, v82, v83
	v_exp_f32_e32 v86, v86
	v_add_f32_e32 v252, v85, v252
	v_mfma_f32_32x32x16_bf16 v[16:31], v[148:151], v[224:227], v[16:31]
	ds_read_b64_tr_b16 v[224:225], v189 offset:0x3400
	ds_read_b64_tr_b16 v[226:227], v189 offset:0x3c00
	s_waitcnt vmcnt(0)
	s_sub_i32 s11, s23, 0x10000
	v_add_u32_e32 v193, s101, v178
	v_add_u32_e32 v194, s101, v179
	v_add_u32_e32 v232, s11, v177
	v_exp_f32_e32 v87, v87
	v_add_f32_e32 v252, v86, v252
	v_cvt_pk_bf16_f32 v236, v84, v85
	v_exp_f32_e32 v88, v88
	v_add_f32_e32 v252, v87, v252
	v_exp_f32_e32 v89, v89
	v_add_f32_e32 v252, v88, v252
	v_cvt_pk_bf16_f32 v237, v86, v87
	s_waitcnt lgkmcnt(4)
	v_mfma_f32_32x32x16_bf16 v[32:47], v[136:139], v[212:215], v[32:47]
	ds_read_b64_tr_b16 v[212:213], v189 offset:0x600
	ds_read_b64_tr_b16 v[214:215], v189 offset:0xe00
	ds_write_b128 v193, v[128:131]
	v_exp_f32_e32 v90, v90
	v_add_f32_e32 v252, v89, v252
	v_exp_f32_e32 v91, v91
	v_permlane32_swap_b32_e32 v234, v236
	v_permlane32_swap_b32_e32 v235, v237
	v_add_f32_e32 v252, v90, v252
	v_cvt_pk_bf16_f32 v238, v88, v89
	v_exp_f32_e32 v92, v92
	v_mfma_f32_32x32x16_bf16 v[32:47], v[140:143], v[216:219], v[32:47]
	ds_read_b64_tr_b16 v[216:217], v189 offset:0x1600
	ds_read_b64_tr_b16 v[218:219], v189 offset:0x1e00
	ds_write_b128 v194, v[124:127]
	v_add_f32_e32 v252, v91, v252
	v_exp_f32_e32 v93, v93
	v_add_f32_e32 v252, v92, v252
	v_cvt_pk_bf16_f32 v239, v90, v91
	v_exp_f32_e32 v94, v94
	v_add_f32_e32 v252, v93, v252
	v_exp_f32_e32 v95, v95
	v_add_f32_e32 v252, v94, v252
	s_waitcnt lgkmcnt(6)
	v_mfma_f32_32x32x16_bf16 v[32:47], v[144:147], v[220:223], v[32:47]
	ds_read_b64_tr_b16 v[220:221], v189 offset:0x2600
	ds_read_b64_tr_b16 v[222:223], v189 offset:0x2e00
	ds_write_b128 v193, v[112:115] offset:16384
	v_cvt_pk_bf16_f32 v240, v92, v93
	v_exp_f32_e32 v64, v64
	v_add_f32_e32 v252, v95, v252
	v_exp_f32_e32 v65, v65
	v_add_f32_e32 v252, v64, v252
	v_cvt_pk_bf16_f32 v241, v94, v95
	v_exp_f32_e32 v66, v66
	v_add_f32_e32 v252, v65, v252
	v_mfma_f32_32x32x16_bf16 v[32:47], v[148:151], v[224:227], v[32:47]
	ds_read_b64_tr_b16 v[224:225], v189 offset:0x3600
	ds_read_b64_tr_b16 v[226:227], v189 offset:0x3e00
	ds_write_b128 v194, v[116:119] offset:16384
	v_exp_f32_e32 v67, v67
	v_permlane32_swap_b32_e32 v238, v240
	v_permlane32_swap_b32_e32 v239, v241
	v_add_f32_e32 v252, v66, v252
	v_cvt_pk_bf16_f32 v242, v64, v65
	v_exp_f32_e32 v68, v68
	v_add_f32_e32 v252, v67, v252
	v_exp_f32_e32 v69, v69
	s_waitcnt lgkmcnt(7)
	v_mfma_f32_32x32x16_bf16 v[48:63], v[136:139], v[212:215], v[48:63]
	ds_write_b128 v232, v[132:135]
	v_add_f32_e32 v252, v68, v252
	v_cvt_pk_bf16_f32 v243, v66, v67
	v_exp_f32_e32 v70, v70
	v_add_f32_e32 v252, v69, v252
	v_exp_f32_e32 v71, v71
	v_add_f32_e32 v252, v70, v252
	v_cvt_pk_bf16_f32 v244, v68, v69
	v_exp_f32_e32 v72, v72
	v_mfma_f32_32x32x16_bf16 v[48:63], v[140:143], v[216:219], v[48:63]
	ds_write_b128 v232, v[120:123] offset:8192
	v_add_f32_e32 v252, v71, v252
	v_exp_f32_e32 v73, v73
	v_add_f32_e32 v252, v72, v252
	v_cvt_pk_bf16_f32 v245, v70, v71
	v_exp_f32_e32 v74, v74
	v_add_f32_e32 v252, v73, v252
	v_exp_f32_e32 v75, v75
	v_permlane32_swap_b32_e32 v242, v244
	s_waitcnt lgkmcnt(3)
	v_mfma_f32_32x32x16_bf16 v[48:63], v[144:147], v[220:223], v[48:63]
	v_permlane32_swap_b32_e32 v243, v245
	v_add_f32_e32 v252, v74, v252
	v_cvt_pk_bf16_f32 v246, v72, v73
	v_exp_f32_e32 v76, v76
	v_add_f32_e32 v252, v75, v252
	v_exp_f32_e32 v77, v77
	v_add_f32_e32 v252, v76, v252
	v_cvt_pk_bf16_f32 v247, v74, v75
	v_exp_f32_e32 v78, v78
	v_mfma_f32_32x32x16_bf16 v[48:63], v[148:151], v[224:227], v[48:63]
	v_add_f32_e32 v252, v77, v252
	v_exp_f32_e32 v79, v79
	v_add_f32_e32 v252, v78, v252
	v_cvt_pk_bf16_f32 v248, v76, v77
	v_add_f32_e32 v252, v79, v252
	v_cvt_pk_bf16_f32 v249, v78, v79
	v_fma_f32 v192, v192, v253, v252
	s_nop 0
	s_nop 0
	v_permlane32_swap_b32_e32 v246, v248
	v_permlane32_swap_b32_e32 v247, v249

.LBB0_107:
	s_sub_i32 s10, 0x20800, s100
	s_sub_i32 s10, s10, s101
	s_sub_i32 s11, 0x44800, s46
	s_sub_i32 s11, s11, s23
	s_mov_b32 s100, s101
	s_mov_b32 s101, s10
	s_mov_b32 s46, s23
	s_mov_b32 s23, s11
	s_add_u32 s40, s40, 0xc0000
	s_addc_u32 s41, s41, 0
	s_cmp_eq_u32 s22, s40
	s_waitcnt lgkmcnt(0)
	s_barrier
	s_cbranch_scc1 .LBB0_111
	s_branch .LBB0_91

.LBB0_111:
	v_mov_b32_e32 v80, 0
	v_mov_b32_e32 v137, 1.0
	v_mov_b32_e32 v206, 0x48f42400
	v_mov_b32_e32 v202, 0x7f800000
	v_mov_b32_e32 v203, 0x37000000
	v_mov_b32_e32 v204, 0xf149f2ca
	v_mov_b32_e32 v205, 1
	v_mov_b32_e32 v210, 0x7fc00000
	s_sub_i32 s10, s46, 0x10000
	v_add_u32_e32 v172, s10, v172
	v_add_u32_e32 v173, s10, v173
	v_add_u32_e32 v174, s10, v174
	v_add_u32_e32 v176, s10, v176
	v_add_u32_e32 v153, s100, v153
	ds_read_b128 v[82:85], v172
	v_xor_b32_e32 v64, 0x80000000, v190
	v_mov_b32_e32 v65, v64
	v_mov_b32_e32 v66, v64
	v_mov_b32_e32 v67, v64
	v_mov_b32_e32 v68, v64
	v_mov_b32_e32 v69, v64
	v_mov_b32_e32 v70, v64
	v_mov_b32_e32 v71, v64
	v_mov_b32_e32 v72, v64
	v_mov_b32_e32 v73, v64
	v_mov_b32_e32 v74, v64
	v_mov_b32_e32 v75, v64
	v_mov_b32_e32 v76, v64
	v_mov_b32_e32 v77, v64
	v_mov_b32_e32 v78, v64
	v_mov_b32_e32 v79, v64
	s_nop 0
	s_nop 0
	s_waitcnt lgkmcnt(0)
	v_mfma_f32_32x32x16_bf16 v[64:79], v[82:85], v[108:111], v[64:79]
	ds_read_b128 v[82:85], v173
	s_nop 0
	s_nop 0
	s_nop 0
	s_nop 0
	s_nop 0
	s_waitcnt lgkmcnt(0)
	v_mfma_f32_32x32x16_bf16 v[64:79], v[82:85], v[104:107], v[64:79]
	ds_read_b128 v[82:85], v174
	ds_read_b128 v[86:89], v176
	s_waitcnt lgkmcnt(1)
	v_mfma_f32_32x32x16_bf16 v[64:79], v[82:85], v[100:103], v[64:79]
	s_nop 0
	s_nop 0
	s_nop 0
	s_nop 0
	s_nop 0
	s_nop 0
	s_nop 0
	s_waitcnt lgkmcnt(0)
	v_mfma_f32_32x32x16_bf16 v[64:79], v[86:89], v[96:99], v[64:79]
	s_nop 0
	s_nop 0
	s_nop 0
	s_nop 0
	s_nop 0
	s_nop 0
	s_nop 5
	s_nop 0
	s_nop 0
	s_nop 0
	s_nop 0
	s_nop 0
	s_nop 0
	s_nop 0
	s_nop 0
	s_sub_i32 s10, 0x20800, s100
	s_sub_i32 s10, s10, s101
	s_add_i32 s10, s10, 0x4000
	v_add_u32_e32 v72, s10, v188
	ds_read_b64_tr_b16 v[94:95], v72 offset:0
	ds_read_b64_tr_b16 v[96:97], v72 offset:0x800
	ds_read_b64_tr_b16 v[98:99], v72 offset:0x1000
	ds_read_b64_tr_b16 v[100:101], v72 offset:0x1800
	ds_read_b64_tr_b16 v[102:103], v72 offset:0x2000
	ds_read_b64_tr_b16 v[104:105], v72 offset:0x2800
	ds_read_b64_tr_b16 v[106:107], v72 offset:0x3000
	ds_read_b64_tr_b16 v[108:109], v72 offset:0x3800
	s_waitcnt lgkmcnt(0)
	s_nop 0
	v_mfma_f32_32x32x16_bf16 v[0:15], v[234:237], v[94:97], v[0:15]
	ds_read_b64_tr_b16 v[94:95], v72 offset:0x200
	ds_read_b64_tr_b16 v[96:97], v72 offset:0xa00
	v_mfma_f32_32x32x16_bf16 v[0:15], v[238:241], v[98:101], v[0:15]
	ds_read_b64_tr_b16 v[98:99], v72 offset:0x1200
	ds_read_b64_tr_b16 v[100:101], v72 offset:0x1a00
	v_mfma_f32_32x32x16_bf16 v[0:15], v[242:245], v[102:105], v[0:15]
	ds_read_b64_tr_b16 v[102:103], v72 offset:0x2200
	ds_read_b64_tr_b16 v[104:105], v72 offset:0x2a00
	v_mfma_f32_32x32x16_bf16 v[0:15], v[246:249], v[106:109], v[0:15]
	ds_read_b64_tr_b16 v[106:107], v72 offset:0x3200
	ds_read_b64_tr_b16 v[108:109], v72 offset:0x3a00
	s_waitcnt lgkmcnt(0)
	v_mfma_f32_32x32x16_bf16 v[16:31], v[234:237], v[94:97], v[16:31]
	ds_read_b64_tr_b16 v[94:95], v72 offset:0x400
	ds_read_b64_tr_b16 v[96:97], v72 offset:0xc00
	v_mfma_f32_32x32x16_bf16 v[16:31], v[238:241], v[98:101], v[16:31]
	ds_read_b64_tr_b16 v[98:99], v72 offset:0x1400
	ds_read_b64_tr_b16 v[100:101], v72 offset:0x1c00
	v_mfma_f32_32x32x16_bf16 v[16:31], v[242:245], v[102:105], v[16:31]
	ds_read_b64_tr_b16 v[102:103], v72 offset:0x2400
	ds_read_b64_tr_b16 v[104:105], v72 offset:0x2c00
	v_mfma_f32_32x32x16_bf16 v[16:31], v[246:249], v[106:109], v[16:31]
	ds_read_b64_tr_b16 v[106:107], v72 offset:0x3400
	ds_read_b64_tr_b16 v[108:109], v72 offset:0x3c00
	s_waitcnt lgkmcnt(0)
	v_mfma_f32_32x32x16_bf16 v[32:47], v[234:237], v[94:97], v[32:47]
	ds_read_b64_tr_b16 v[94:95], v72 offset:0x600
	ds_read_b64_tr_b16 v[96:97], v72 offset:0xe00
	v_mfma_f32_32x32x16_bf16 v[32:47], v[238:241], v[98:101], v[32:47]
	ds_read_b64_tr_b16 v[98:99], v72 offset:0x1600
	ds_read_b64_tr_b16 v[100:101], v72 offset:0x1e00
	v_mfma_f32_32x32x16_bf16 v[32:47], v[242:245], v[102:105], v[32:47]
	ds_read_b64_tr_b16 v[102:103], v72 offset:0x2600
	ds_read_b64_tr_b16 v[104:105], v72 offset:0x2e00
	v_mfma_f32_32x32x16_bf16 v[32:47], v[246:249], v[106:109], v[32:47]
	ds_read_b64_tr_b16 v[106:107], v72 offset:0x3600
	ds_read_b64_tr_b16 v[108:109], v72 offset:0x3e00
	s_waitcnt lgkmcnt(0)
	v_mfma_f32_32x32x16_bf16 v[48:63], v[234:237], v[94:97], v[48:63]
	v_max3_f32 v72, v64, v65, v66
	v_max3_f32 v72, v72, v67, v68
	v_max3_f32 v72, v72, v69, v70
	v_mov_b32_e32 v73, 0xf149f2ca
	v_max3_f32 v72, v72, v71, v73
	v_mov_b32_e32 v78, v72
	s_nop 1
	v_permlane32_swap_b32_e32 v72, v78
	v_mfma_f32_32x32x16_bf16 v[48:63], v[238:241], v[98:101], v[48:63]
	v_max_f32_e32 v72, v72, v72
	v_mov_b32_e32 v211, v206
	v_mfma_f32_32x32x16_bf16 v[48:63], v[242:245], v[102:105], v[48:63]
	v_max_f32_e32 v74, v78, v78
	v_max_f32_e32 v74, v72, v74
	v_cmp_ge_f32_e32 vcc, s63, v74
	s_cmp_eq_u64 vcc, exec
	v_mov_b32_e32 v72, 1.0
	v_mfma_f32_32x32x16_bf16 v[48:63], v[246:249], v[106:109], v[48:63]
	s_cbranch_scc0 .LBB0_147
	v_cmp_gt_f32_e32 vcc, 1.0, v72
	s_cbranch_vccz .LBB0_116

	.amdhsa_kernel _Z16hymba_megakernel6Params
		.amdhsa_group_segment_fixed_size 18432
		.amdhsa_private_segment_fixed_size 0
		.amdhsa_kernarg_size 480
		.amdhsa_user_sgpr_count 2
		.amdhsa_user_sgpr_dispatch_ptr 0
		.amdhsa_user_sgpr_queue_ptr 0
		.amdhsa_user_sgpr_kernarg_segment_ptr 1
		.amdhsa_user_sgpr_dispatch_id 0
		.amdhsa_user_sgpr_kernarg_preload_length 0
		.amdhsa_user_sgpr_kernarg_preload_offset 0
		.amdhsa_user_sgpr_private_segment_size 0
		.amdhsa_uses_dynamic_stack 0
		.amdhsa_enable_private_segment 0
		.amdhsa_system_sgpr_workgroup_id_x 1
		.amdhsa_system_sgpr_workgroup_id_y 0
		.amdhsa_system_sgpr_workgroup_id_z 0
		.amdhsa_system_sgpr_workgroup_info 0
		.amdhsa_system_vgpr_workitem_id 2
		.amdhsa_next_free_vgpr 256
		.amdhsa_next_free_sgpr 102
		.amdhsa_accum_offset 256
		.amdhsa_reserve_vcc 1
		.amdhsa_float_round_mode_32 0
		.amdhsa_float_round_mode_16_64 0
		.amdhsa_float_denorm_mode_32 3
		.amdhsa_float_denorm_mode_16_64 3
		.amdhsa_dx10_clamp 1
		.amdhsa_ieee_mode 1
		.amdhsa_fp16_overflow 0
		.amdhsa_tg_split 0
		.amdhsa_exception_fp_ieee_invalid_op 0
		.amdhsa_exception_fp_denorm_src 0
		.amdhsa_exception_fp_ieee_div_zero 0
		.amdhsa_exception_fp_ieee_overflow 0
		.amdhsa_exception_fp_ieee_underflow 0
		.amdhsa_exception_fp_ieee_inexact 0
		.amdhsa_exception_int_div_zero 0
	.end_amdhsa_kernel

amdhsa.kernels:
  - .agpr_count:     0
    .args:
      - .offset:         0
        .size:           224
        .value_kind:     by_value
      - .offset:         224
        .size:           4
        .value_kind:     hidden_block_count_x
      - .offset:         228
        .size:           4
        .value_kind:     hidden_block_count_y
      - .offset:         232
        .size:           4
        .value_kind:     hidden_block_count_z
      - .offset:         236
        .size:           2
        .value_kind:     hidden_group_size_x
      - .offset:         238
        .size:           2
        .value_kind:     hidden_group_size_y
      - .offset:         240
        .size:           2
        .value_kind:     hidden_group_size_z
      - .offset:         242
        .size:           2
        .value_kind:     hidden_remainder_x
      - .offset:         244
        .size:           2
        .value_kind:     hidden_remainder_y
      - .offset:         246
        .size:           2
        .value_kind:     hidden_remainder_z
      - .offset:         264
        .size:           8
        .value_kind:     hidden_global_offset_x
      - .offset:         272
        .size:           8
        .value_kind:     hidden_global_offset_y
      - .offset:         280
        .size:           8
        .value_kind:     hidden_global_offset_z
      - .offset:         288
        .size:           2
        .value_kind:     hidden_grid_dims
      - .offset:         312
        .size:           8
        .value_kind:     hidden_multigrid_sync_arg
      - .offset:         344
        .size:           4
        .value_kind:     hidden_dynamic_lds_size
    .group_segment_fixed_size: 18432
    .kernarg_segment_align: 8
    .kernarg_segment_size: 480
    .language:       OpenCL C
    .language_version:
      - 2
      - 0
    .max_flat_workgroup_size: 512
    .name:           _Z16hymba_megakernel6Params
    .private_segment_fixed_size: 0
    .sgpr_count:     108
    .sgpr_spill_count: 84
    .symbol:         _Z16hymba_megakernel6Params.kd
    .uniform_work_group_size: 1
    .uses_dynamic_stack: false
    .vgpr_count:     256
    .vgpr_spill_count: 0
    .wavefront_size: 64
